# P4 cross-row sums (lane^16, lane^32) via v_permlane16_swap / v_permlane32_swap copies instead of ds_bpermute round trips (10 chains per item), same summation order
# baseline (speedup 1.0000x reference)
.LBB0_586:
	s_or_b64 exec, exec, s[0:1]
	v_add_f32_e32 v50, v54, v48
	v_add_f32_e32 v51, v53, v49
	v_add_f32_e32 v50, v50, v51
	v_mov_b32_e32 v51, v50
	s_nop 1
	v_permlane16_swap_b32 v51, v50
	v_add_f32_e32 v50, v50, v51
	s_waitcnt lgkmcnt(0)
	v_mov_b32_e32 v51, v50
	s_nop 1
	v_permlane32_swap_b32 v51, v50
	v_add_f32_e32 v50, v50, v51
	s_and_saveexec_b64 s[0:1], s[56:57]
	s_cbranch_execz .LBB0_588
	s_waitcnt lgkmcnt(0)
	ds_add_f32 v122, v50

.LBB0_595:
	s_or_b64 exec, exec, s[0:1]
	v_add_f32_e32 v50, v54, v48
	s_waitcnt lgkmcnt(1)
	v_add_f32_e32 v51, v53, v49
	v_add_f32_e32 v50, v50, v51
	v_mov_b32_e32 v51, v50
	s_nop 1
	v_permlane16_swap_b32 v51, v50
	v_add_f32_e32 v50, v50, v51
	s_waitcnt lgkmcnt(0)
	v_mov_b32_e32 v51, v50
	s_nop 1
	v_permlane32_swap_b32 v51, v50
	v_add_f32_e32 v50, v50, v51
	s_and_saveexec_b64 s[0:1], s[60:61]
	s_cbranch_execz .LBB0_597
	s_waitcnt lgkmcnt(0)
	ds_add_f32 v122, v50

.LBB0_599:
	s_or_b64 exec, exec, s[0:1]
	s_waitcnt lgkmcnt(0)
	s_barrier
	ds_read_b128 v[56:59], v185 offset:53248
	ds_read_b128 v[60:63], v185 offset:53312
	ds_read_b128 v[48:51], v187
	ds_read_b128 v[52:55], v187 offset:64
	s_waitcnt lgkmcnt(1)
	v_mfma_f32_16x16x32_bf16 v[64:67], v[56:59], v[48:51], 0
	ds_read_b128 v[68:71], v185 offset:53376
	ds_read_b128 v[48:51], v185 offset:53440
	s_waitcnt lgkmcnt(2)
	v_mfma_f32_16x16x32_bf16 v[52:55], v[60:63], v[52:55], v[64:67]
	s_nop 3
	ds_read_b128 v[64:67], v187 offset:128
	ds_read_b128 v[188:191], v187 offset:192
	s_waitcnt lgkmcnt(1)
	v_mfma_f32_16x16x32_bf16 v[64:67], v[68:71], v[64:67], v[52:55]
	s_nop 2
	ds_read_b128 v[52:55], v143 offset:34816
	ds_read_b128 v[192:195], v186
	s_waitcnt lgkmcnt(2)
	v_mfma_f32_16x16x32_bf16 v[188:191], v[48:51], v[188:191], v[64:67]
	ds_read_b32 v77, v145
	ds_read_b32 v81, v146
	ds_read_b32 v83, v147
	ds_read_b32 v200, v148
	ds_read_b128 v[64:67], v144 offset:34816
	ds_read_b128 v[196:199], v186 offset:64
	s_waitcnt lgkmcnt(3)
	v_fmac_f32_e32 v81, v77, v83
	s_waitcnt lgkmcnt(2)
	v_max_f32_e32 v83, v200, v200
	v_max_f32_e64 v81, |v81|, v83
	v_mfma_f32_16x16x32_bf16 v[192:195], v[52:55], v[192:195], 0
	s_waitcnt lgkmcnt(0)
	v_mfma_f32_16x16x32_bf16 v[196:199], v[64:67], v[196:199], v[192:195]
	s_nop 4
	v_rcp_f32_e32 v216, v81
	s_nop 0
	v_fma_f32 v217, -v81, v216, 1.0
	v_fmac_f32_e32 v216, v217, v216
	v_mul_f32_e32 v217, 1.0, v216
	v_div_fixup_f32 v81, v217, v81, 1.0
	v_fma_f32 v83, v188, v77, v196
	v_fma_f32 v188, v189, v77, v197
	v_mul_f32_e32 v196, v83, v81
	v_fma_f32 v83, v83, v81, 0
	v_mul_f32_e32 v194, v188, v81
	v_fmac_f32_e32 v83, v188, v81
	v_mul_f32_e32 v188, v194, v194
	v_fma_f32 v189, v190, v77, v198
	v_fmac_f32_e32 v188, v196, v196
	v_mul_f32_e32 v192, v189, v81
	v_fmac_f32_e32 v199, v191, v77
	v_fmac_f32_e32 v83, v189, v81
	v_fmac_f32_e32 v188, v192, v192
	v_mul_f32_e32 v190, v199, v81
	v_fmac_f32_e32 v83, v199, v81
	v_fmac_f32_e32 v188, v190, v190
	v_mov_b32_e32 v77, v83
	s_nop 1
	v_permlane16_swap_b32 v77, v83
	v_add_f32_e32 v77, v83, v77
	v_mov_b32_e32 v189, v188
	s_nop 1
	v_permlane16_swap_b32 v189, v188
	v_add_f32_e32 v83, v188, v189
	s_waitcnt lgkmcnt(1)
	s_waitcnt lgkmcnt(0)
	v_mov_b32_e32 v81, v77
	s_nop 1
	v_permlane32_swap_b32 v81, v77
	v_add_f32_e32 v77, v77, v81
	v_mov_b32_e32 v188, v83
	s_nop 1
	v_permlane32_swap_b32 v188, v83
	v_add_f32_e32 v83, v83, v188
	s_and_saveexec_b64 s[0:1], s[12:13]
	s_cbranch_execz .LBB0_601
	s_waitcnt lgkmcnt(1)
	s_waitcnt lgkmcnt(0)
	ds_add_f32 v126, v77
	ds_add_f32 v149, v83
.LBB0_601:
	s_or_b64 exec, exec, s[0:1]
	ds_read_b128 v[198:201], v187 offset:4352
	ds_read_b128 v[202:205], v187 offset:4416
	s_waitcnt lgkmcnt(1)
	v_mfma_f32_16x16x32_bf16 v[198:201], v[56:59], v[198:201], 0
	s_waitcnt lgkmcnt(0)
	v_mfma_f32_16x16x32_bf16 v[198:201], v[60:63], v[202:205], v[198:201]
	ds_read_b128 v[202:205], v187 offset:4480
	ds_read_b128 v[206:209], v187 offset:4544
	s_waitcnt lgkmcnt(1)
	v_mfma_f32_16x16x32_bf16 v[198:201], v[68:71], v[202:205], v[198:201]
	ds_read_b32 v77, v151
	ds_read_b32 v81, v152
	ds_read_b32 v83, v153
	ds_read_b32 v188, v154
	ds_read_b128 v[202:205], v186 offset:2304
	ds_read_b128 v[210:213], v186 offset:2368
	s_waitcnt lgkmcnt(3)
	v_fmac_f32_e32 v81, v77, v83
	s_waitcnt lgkmcnt(2)
	v_max_f32_e32 v83, v188, v188
	v_max_f32_e64 v81, |v81|, v83
	s_waitcnt lgkmcnt(1)
	v_mfma_f32_16x16x32_bf16 v[202:205], v[52:55], v[202:205], 0
	v_mfma_f32_16x16x32_bf16 v[198:201], v[48:51], v[206:209], v[198:201]
	s_waitcnt lgkmcnt(0)
	v_mfma_f32_16x16x32_bf16 v[202:205], v[64:67], v[210:213], v[202:205]
	v_rcp_f32_e32 v216, v81
	s_nop 0
	v_fma_f32 v217, -v81, v216, 1.0
	v_fmac_f32_e32 v216, v217, v216
	v_mul_f32_e32 v217, 1.0, v216
	v_div_fixup_f32 v83, v217, v81, 1.0
	s_nop 5
	v_fma_f32 v81, v198, v77, v202
	v_mul_f32_e32 v195, v81, v83
	v_fma_f32 v189, v81, v83, 0
	v_fma_f32 v81, v199, v77, v203
	v_mul_f32_e32 v191, v81, v83
	v_fmac_f32_e32 v189, v81, v83
	v_mul_f32_e32 v193, v191, v191
	v_fma_f32 v81, v200, v77, v204
	v_fmac_f32_e32 v193, v195, v195
	v_mul_f32_e32 v188, v81, v83
	v_fmac_f32_e32 v205, v201, v77
	v_fmac_f32_e32 v189, v81, v83
	v_fmac_f32_e32 v193, v188, v188
	v_mul_f32_e32 v81, v205, v83
	v_fmac_f32_e32 v189, v205, v83
	v_fmac_f32_e32 v193, v81, v81
	v_mov_b32_e32 v77, v189
	s_nop 1
	v_permlane16_swap_b32 v77, v189
	v_add_f32_e32 v77, v189, v77
	v_mov_b32_e32 v197, v193
	s_nop 1
	v_permlane16_swap_b32 v197, v193
	v_add_f32_e32 v189, v193, v197
	s_waitcnt lgkmcnt(1)
	s_waitcnt lgkmcnt(0)
	v_mov_b32_e32 v83, v77
	s_nop 1
	v_permlane32_swap_b32 v83, v77
	v_add_f32_e32 v77, v77, v83
	v_mov_b32_e32 v193, v189
	s_nop 1
	v_permlane32_swap_b32 v193, v189
	v_add_f32_e32 v189, v189, v193
	s_and_saveexec_b64 s[0:1], s[12:13]
	s_cbranch_execz .LBB0_603
	s_waitcnt lgkmcnt(1)
	s_waitcnt lgkmcnt(0)
	ds_add_f32 v156, v77
	ds_add_f32 v155, v189
.LBB0_603:
	s_or_b64 exec, exec, s[0:1]
	ds_read_b128 v[198:201], v187 offset:8704
	ds_read_b128 v[202:205], v187 offset:8768
	s_waitcnt lgkmcnt(1)
	v_mfma_f32_16x16x32_bf16 v[198:201], v[56:59], v[198:201], 0
	s_waitcnt lgkmcnt(0)
	v_mfma_f32_16x16x32_bf16 v[198:201], v[60:63], v[202:205], v[198:201]
	ds_read_b128 v[202:205], v187 offset:8832
	ds_read_b128 v[206:209], v187 offset:8896
	s_waitcnt lgkmcnt(1)
	v_mfma_f32_16x16x32_bf16 v[198:201], v[68:71], v[202:205], v[198:201]
	ds_read_b32 v77, v158
	ds_read_b32 v83, v159
	ds_read_b32 v189, v160
	ds_read_b32 v193, v161
	ds_read_b128 v[202:205], v186 offset:4608
	ds_read_b128 v[210:213], v186 offset:4672
	s_waitcnt lgkmcnt(3)
	v_fmac_f32_e32 v83, v77, v189
	s_waitcnt lgkmcnt(2)
	v_max_f32_e32 v189, v193, v193
	v_max_f32_e64 v83, |v83|, v189
	s_waitcnt lgkmcnt(1)
	v_mfma_f32_16x16x32_bf16 v[202:205], v[52:55], v[202:205], 0
	v_mfma_f32_16x16x32_bf16 v[198:201], v[48:51], v[206:209], v[198:201]
	s_waitcnt lgkmcnt(0)
	v_mfma_f32_16x16x32_bf16 v[202:205], v[64:67], v[210:213], v[202:205]
	v_rcp_f32_e32 v216, v83
	s_nop 0
	v_fma_f32 v217, -v83, v216, 1.0
	v_fmac_f32_e32 v216, v217, v216
	v_mul_f32_e32 v217, 1.0, v216
	v_div_fixup_f32 v197, v217, v83, 1.0
	s_nop 4
	v_fma_f32 v83, v198, v77, v202
	v_mul_f32_e32 v193, v83, v197
	v_fma_f32 v198, v83, v197, 0
	v_fma_f32 v83, v199, v77, v203
	v_mul_f32_e32 v189, v83, v197
	v_mul_f32_e32 v199, v189, v189
	v_fma_f32 v200, v200, v77, v204
	v_fmac_f32_e32 v198, v83, v197
	v_fmac_f32_e32 v199, v193, v193
	v_mul_f32_e32 v83, v200, v197
	v_fmac_f32_e32 v205, v201, v77
	v_fmac_f32_e32 v198, v200, v197
	v_fmac_f32_e32 v199, v83, v83
	v_mul_f32_e32 v77, v205, v197
	v_fmac_f32_e32 v198, v205, v197
	v_fmac_f32_e32 v199, v77, v77
	v_mov_b32_e32 v197, v198
	s_nop 1
	v_permlane16_swap_b32 v197, v198
	v_add_f32_e32 v197, v198, v197
	v_mov_b32_e32 v200, v199
	s_nop 1
	v_permlane16_swap_b32 v200, v199
	v_add_f32_e32 v199, v199, v200
	s_waitcnt lgkmcnt(1)
	s_waitcnt lgkmcnt(0)
	v_mov_b32_e32 v198, v197
	s_nop 1
	v_permlane32_swap_b32 v198, v197
	v_add_f32_e32 v197, v197, v198
	v_mov_b32_e32 v200, v199
	s_nop 1
	v_permlane32_swap_b32 v200, v199
	v_add_f32_e32 v199, v199, v200
	s_and_saveexec_b64 s[0:1], s[12:13]
	s_cbranch_execz .LBB0_605
	s_waitcnt lgkmcnt(1)
	s_waitcnt lgkmcnt(0)
	ds_add_f32 v163, v197
	ds_add_f32 v162, v199
.LBB0_605:
	s_or_b64 exec, exec, s[0:1]
	s_waitcnt lgkmcnt(0)
	ds_read_b128 v[198:201], v187 offset:13056
	ds_read_b128 v[202:205], v187 offset:13120
	s_waitcnt lgkmcnt(1)
	v_mfma_f32_16x16x32_bf16 v[56:59], v[56:59], v[198:201], 0
	s_waitcnt lgkmcnt(0)
	v_mfma_f32_16x16x32_bf16 v[56:59], v[60:63], v[202:205], v[56:59]
	ds_read_b128 v[60:63], v187 offset:13184
	ds_read_b128 v[198:201], v187 offset:13248
	s_waitcnt lgkmcnt(1)
	v_mfma_f32_16x16x32_bf16 v[56:59], v[68:71], v[60:63], v[56:59]
	ds_read_b32 v197, v165
	ds_read_b32 v202, v166
	ds_read_b32 v203, v167
	ds_read_b32 v204, v168
	ds_read_b128 v[60:63], v186 offset:6912
	ds_read_b128 v[68:71], v186 offset:6976
	s_waitcnt lgkmcnt(3)
	v_fmac_f32_e32 v202, v197, v203
	v_mfma_f32_16x16x32_bf16 v[48:51], v[48:51], v[198:201], v[56:59]
	s_waitcnt lgkmcnt(2)
	s_nop 1
	v_max_f32_e32 v56, v204, v204
	v_max_f32_e64 v56, |v202|, v56
	s_waitcnt lgkmcnt(1)
	v_mfma_f32_16x16x32_bf16 v[52:55], v[52:55], v[60:63], 0
	s_waitcnt lgkmcnt(0)
	v_mfma_f32_16x16x32_bf16 v[52:55], v[64:67], v[68:71], v[52:55]
	v_rcp_f32_e32 v216, v56
	s_nop 0
	v_fma_f32 v217, -v56, v216, 1.0
	v_fmac_f32_e32 v216, v217, v216
	v_mul_f32_e32 v217, 1.0, v216
	v_div_fixup_f32 v60, v217, v56, 1.0
	s_nop 2
	v_fma_f32 v48, v48, v197, v52
	v_fma_f32 v49, v49, v197, v53
	v_mul_f32_e32 v59, v48, v60
	v_fma_f32 v48, v48, v60, 0
	v_mul_f32_e32 v58, v49, v60
	v_fmac_f32_e32 v48, v49, v60
	v_mul_f32_e32 v52, v58, v58
	v_fma_f32 v49, v50, v197, v54
	v_fmac_f32_e32 v52, v59, v59
	v_mul_f32_e32 v57, v49, v60
	v_fmac_f32_e32 v55, v51, v197
	v_fmac_f32_e32 v48, v49, v60
	v_fmac_f32_e32 v52, v57, v57
	v_mul_f32_e32 v56, v55, v60
	v_fmac_f32_e32 v48, v55, v60
	v_fmac_f32_e32 v52, v56, v56
	v_mov_b32_e32 v49, v48
	s_nop 1
	v_permlane16_swap_b32 v49, v48
	v_add_f32_e32 v48, v48, v49
	v_mov_b32_e32 v50, v52
	s_nop 1
	v_permlane16_swap_b32 v50, v52
	v_add_f32_e32 v50, v52, v50
	s_waitcnt lgkmcnt(1)
	s_waitcnt lgkmcnt(0)
	v_mov_b32_e32 v49, v48
	s_nop 1
	v_permlane32_swap_b32 v49, v48
	v_add_f32_e32 v48, v48, v49
	v_mov_b32_e32 v51, v50
	s_nop 1
	v_permlane32_swap_b32 v51, v50
	v_add_f32_e32 v50, v50, v51
	s_and_saveexec_b64 s[0:1], s[12:13]
	s_cbranch_execz .LBB0_570
	s_waitcnt lgkmcnt(1)
	s_waitcnt lgkmcnt(0)
	ds_add_f32 v170, v48
	ds_add_f32 v169, v50
	s_branch .LBB0_570
